# grid barrier poll: all 16 arrival-counter loads addressed from one base with immediate offsets and issued back to back (one round trip per poll instead of four)
# speedup vs baseline: 1.0056x; 1.0056x over previous
.LBB0_259:
	s_waitcnt lgkmcnt(0)
	global_load_dword v13, v0, s[80:81] sc1
	global_load_dword v1, v0, s[82:83] sc1
	global_load_dword v2, v0, s[84:85] sc1
	global_load_dword v3, v0, s[86:87] sc1
	global_load_dword v8, v0, s[88:89] sc1
	global_load_dword v9, v0, s[90:91] sc1
	global_load_dword v10, v0, s[60:61] sc1
	global_load_dword v11, v0, s[56:57] sc1
	global_load_dword v12, v0, s[58:59] sc1
	global_load_dword v14, v0, s[80:81] offset:2304 sc1
	global_load_dword v15, v0, s[80:81] offset:2560 sc1
	global_load_dword v16, v0, s[80:81] offset:2816 sc1
	global_load_dword v17, v0, s[80:81] offset:3072 sc1
	global_load_dword v18, v0, s[80:81] offset:3328 sc1
	global_load_dword v19, v0, s[80:81] offset:3584 sc1
	global_load_dword v20, v0, s[80:81] offset:3840 sc1
	s_mov_b64 s[6:7], -1
	s_mov_b64 s[4:5], -1
	s_waitcnt vmcnt(0)
	v_add_u32_e32 v21, v1, v13
	v_add_u32_e32 v21, v21, v2
	v_add_u32_e32 v21, v21, v3
	v_add_u32_e32 v21, v21, v8
	v_add_u32_e32 v21, v21, v9
	v_add_u32_e32 v21, v21, v10
	v_add_u32_e32 v21, v21, v11
	v_add_u32_e32 v21, v21, v12
	v_add_u32_e32 v21, v21, v14
	v_add_u32_e32 v21, v21, v15
	v_add_u32_e32 v21, v21, v16
	v_add_u32_e32 v21, v21, v17
	v_add_u32_e32 v21, v21, v18
	v_add_u32_e32 v21, v21, v19
	v_add_u32_e32 v21, v21, v20
	v_cmp_eq_u32_e32 vcc, s77, v21
	s_cbranch_vccnz .LBB0_258
	s_and_b32 s4, s10, 0xff
	s_cmp_eq_u32 s4, 0
	s_mov_b64 s[4:5], -1
	s_mov_b64 s[8:9], -1
	s_sleep 1
	s_cbranch_scc0 .LBB0_263
	global_load_dword v21, v0, s[78:79] sc1
	s_waitcnt vmcnt(0)
	v_cmp_eq_u32_e32 vcc, 0, v21
	s_cbranch_vccnz .LBB0_265
	s_mov_b64 s[8:9], 0

.LBB0_554:
	s_waitcnt lgkmcnt(0)
	global_load_dword v13, v0, s[80:81] sc1
	global_load_dword v1, v0, s[82:83] sc1
	global_load_dword v2, v0, s[84:85] sc1
	global_load_dword v3, v0, s[86:87] sc1
	global_load_dword v8, v0, s[88:89] sc1
	global_load_dword v9, v0, s[90:91] sc1
	global_load_dword v10, v0, s[60:61] sc1
	global_load_dword v11, v0, s[56:57] sc1
	global_load_dword v12, v0, s[58:59] sc1
	global_load_dword v14, v0, s[80:81] offset:2304 sc1
	global_load_dword v15, v0, s[80:81] offset:2560 sc1
	global_load_dword v16, v0, s[80:81] offset:2816 sc1
	global_load_dword v17, v0, s[80:81] offset:3072 sc1
	global_load_dword v18, v0, s[80:81] offset:3328 sc1
	global_load_dword v19, v0, s[80:81] offset:3584 sc1
	global_load_dword v20, v0, s[80:81] offset:3840 sc1
	s_mov_b64 s[4:5], -1
	s_mov_b64 s[2:3], -1
	s_waitcnt vmcnt(0)
	v_add_u32_e32 v21, v1, v13
	v_add_u32_e32 v21, v21, v2
	v_add_u32_e32 v21, v21, v3
	v_add_u32_e32 v21, v21, v8
	v_add_u32_e32 v21, v21, v9
	v_add_u32_e32 v21, v21, v10
	v_add_u32_e32 v21, v21, v11
	v_add_u32_e32 v21, v21, v12
	v_add_u32_e32 v21, v21, v14
	v_add_u32_e32 v21, v21, v15
	v_add_u32_e32 v21, v21, v16
	v_add_u32_e32 v21, v21, v17
	v_add_u32_e32 v21, v21, v18
	v_add_u32_e32 v21, v21, v19
	v_add_u32_e32 v21, v21, v20
	v_cmp_eq_u32_e32 vcc, s77, v21
	s_cbranch_vccnz .LBB0_553
	s_and_b32 s2, s8, 0xff
	s_cmp_eq_u32 s2, 0
	s_mov_b64 s[2:3], -1
	s_mov_b64 s[6:7], -1
	s_sleep 1
	s_cbranch_scc0 .LBB0_558
	global_load_dword v21, v0, s[78:79] sc1
	s_waitcnt vmcnt(0)
	v_cmp_eq_u32_e32 vcc, 0, v21
	s_cbranch_vccnz .LBB0_560
	s_mov_b64 s[6:7], 0
